# P3: GEMM accumulators initialised with x (nt loads issued around grid barrier 3); epilogue no longer loads x
# speedup vs baseline: 1.0081x; 1.0022x over previous
.LBB0_311:
	s_waitcnt vmcnt(0)
	s_waitcnt lgkmcnt(0)
	s_barrier
	s_cmpk_gt_u32 s2, 0xff
	s_cbranch_scc1 .Lxa_skip
	v_readfirstlane_b32 s4, v254
	s_and_b32 s5, s2, 7
	s_lshr_b32 s4, s4, 6
	s_lshl_b32 s5, s5, 3
	s_bfe_u32 s6, s2, 0x30003
	s_add_i32 s5, s5, s6
	s_lshr_b32 s6, s2, 6
	s_lshl_b32 s5, s5, 8
	s_lshr_b32 s7, s4, 2
	s_lshl_b32 s7, s7, 6
	s_add_i32 s5, s5, s7
	s_lshl_b32 s6, s6, 8
	s_and_b32 s7, s4, 3
	s_lshl_b32 s7, s7, 6
	s_add_i32 s6, s6, s7
	v_and_b32_e32 v200, 15, v254
	v_bfe_u32 v201, v254, 4, 2
	v_or_b32_e32 v200, s5, v200
	v_lshl_or_b32 v201, v201, 3, s6
	v_lshlrev_b32_e32 v200, 10, v200
	v_add_u32_e32 v200, v200, v201
	v_lshlrev_b32_e32 v200, 2, v200
	v_add_u32_e32 v201, 0x10000, v200
	v_add_u32_e32 v202, 0x20000, v200
	v_add_u32_e32 v203, 0x30000, v200
	v_add_u32_e32 v204, 0x80000, v200
	v_add_u32_e32 v205, 0x90000, v200
	v_add_u32_e32 v206, 0xa0000, v200
	v_add_u32_e32 v207, 0xb0000, v200
	s_cmp_eq_u32 s4, 0
	s_cbranch_scc1 .Lxa_skip
	global_load_dwordx4 v[124:127], v200, s[12:13] nt
	global_load_dwordx4 v[120:123], v200, s[12:13] offset:16 nt
	global_load_dwordx4 v[116:119], v200, s[12:13] offset:128 nt
	global_load_dwordx4 v[112:115], v200, s[12:13] offset:144 nt
	global_load_dwordx4 v[108:111], v201, s[12:13] nt
	global_load_dwordx4 v[104:107], v201, s[12:13] offset:16 nt
	global_load_dwordx4 v[100:103], v201, s[12:13] offset:128 nt
	global_load_dwordx4 v[96:99], v201, s[12:13] offset:144 nt
	global_load_dwordx4 v[92:95], v202, s[12:13] nt
	global_load_dwordx4 v[88:91], v202, s[12:13] offset:16 nt
	global_load_dwordx4 v[84:87], v202, s[12:13] offset:128 nt
	global_load_dwordx4 v[80:83], v202, s[12:13] offset:144 nt
	global_load_dwordx4 v[76:79], v203, s[12:13] nt
	global_load_dwordx4 v[72:75], v203, s[12:13] offset:16 nt
	global_load_dwordx4 v[68:71], v203, s[12:13] offset:128 nt
	global_load_dwordx4 v[64:67], v203, s[12:13] offset:144 nt
	global_load_dwordx4 v[60:63], v204, s[12:13] nt
	global_load_dwordx4 v[56:59], v204, s[12:13] offset:16 nt
	global_load_dwordx4 v[52:55], v204, s[12:13] offset:128 nt
	global_load_dwordx4 v[48:51], v204, s[12:13] offset:144 nt
	global_load_dwordx4 v[44:47], v205, s[12:13] nt
	global_load_dwordx4 v[40:43], v205, s[12:13] offset:16 nt
	global_load_dwordx4 v[36:39], v205, s[12:13] offset:128 nt
	global_load_dwordx4 v[32:35], v205, s[12:13] offset:144 nt
	global_load_dwordx4 v[28:31], v206, s[12:13] nt
	global_load_dwordx4 v[24:27], v206, s[12:13] offset:16 nt
	global_load_dwordx4 v[20:23], v206, s[12:13] offset:128 nt
.Lxa_skip:
	s_and_saveexec_b64 s[0:1], s[92:93]
	s_cbranch_execz .LBB0_363
	s_add_i32 s4, 0, 0x20020
	v_mov_b32_e32 v0, s4
	s_waitcnt vmcnt(0) expcnt(0) lgkmcnt(0)
	ds_read_b32 v2, v0
	s_add_i32 s4, 0, 0x20024
	v_mov_b32_e32 v0, s4
	ds_read_b32 v0, v0
	s_waitcnt lgkmcnt(1)
	v_cmp_ne_u32_e32 vcc, 0, v2
	s_cbranch_vccnz .LBB0_327
	s_add_u32 s4, s52, 0x1200
	s_addc_u32 s5, s53, 0
	s_add_u32 s6, s52, 0x1400
	s_addc_u32 s7, s53, 0
	s_add_u32 s20, s52, 0x1500
	s_addc_u32 s21, s53, 0
	s_add_u32 s22, s52, 0x1600
	s_addc_u32 s23, s53, 0
	s_add_u32 s24, s52, 0x1700
	s_addc_u32 s25, s53, 0
	s_add_u32 s26, s52, 0x1800
	s_addc_u32 s27, s53, 0
	s_add_u32 s36, s52, 0x1900
	s_addc_u32 s37, s53, 0
	s_add_u32 s38, s52, 0x1a00
	s_addc_u32 s39, s53, 0
	s_add_u32 s40, s52, 0x1b00
	s_addc_u32 s41, s53, 0
	s_add_u32 s44, s52, 0x1c00
	s_addc_u32 s45, s53, 0
	s_add_u32 s46, s52, 0x1d00
	s_addc_u32 s47, s53, 0
	s_add_u32 s48, s52, 0x1e00
	s_addc_u32 s49, s53, 0
	s_add_u32 s50, s52, 0x1f00
	s_addc_u32 s51, s53, 0
	s_add_u32 s56, s52, 0x2000
	s_addc_u32 s57, s53, 0
	s_add_u32 s58, s52, 0x2100
	s_addc_u32 s59, s53, 0
	s_add_u32 s60, s52, 0x2200
	s_addc_u32 s61, s53, 0
	s_mul_i32 s70, s11, s33
	s_add_u32 s62, s52, 0x2300
	s_mul_i32 s70, s70, s10
	s_addc_u32 s63, s53, 0
	s_mov_b32 s71, 1
	v_mov_b32_e32 v16, 0
	s_branch .LBB0_315

.LBB0_363:
	s_or_b64 exec, exec, s[0:1]
	s_waitcnt vmcnt(1)
	v_mov_b32_e32 v144, v254
	s_waitcnt lgkmcnt(0)
	v_cndmask_b32_e64 v240, 0, 1, s[94:95]
	s_barrier
	s_cmpk_gt_u32 s2, 0xff
	s_cbranch_scc1 .Lxb_done
	v_readfirstlane_b32 s4, v254
	s_nop 0
	s_lshr_b32 s4, s4, 6
	s_cmp_lg_u32 s4, 0
	s_cbranch_scc1 .Lxb_low
	global_load_dwordx4 v[124:127], v200, s[12:13] nt
	global_load_dwordx4 v[120:123], v200, s[12:13] offset:16 nt
	global_load_dwordx4 v[116:119], v200, s[12:13] offset:128 nt
	global_load_dwordx4 v[112:115], v200, s[12:13] offset:144 nt
	global_load_dwordx4 v[108:111], v201, s[12:13] nt
	global_load_dwordx4 v[104:107], v201, s[12:13] offset:16 nt
	global_load_dwordx4 v[100:103], v201, s[12:13] offset:128 nt
	global_load_dwordx4 v[96:99], v201, s[12:13] offset:144 nt
	global_load_dwordx4 v[92:95], v202, s[12:13] nt
	global_load_dwordx4 v[88:91], v202, s[12:13] offset:16 nt
	global_load_dwordx4 v[84:87], v202, s[12:13] offset:128 nt
	global_load_dwordx4 v[80:83], v202, s[12:13] offset:144 nt
	global_load_dwordx4 v[76:79], v203, s[12:13] nt
	global_load_dwordx4 v[72:75], v203, s[12:13] offset:16 nt
	global_load_dwordx4 v[68:71], v203, s[12:13] offset:128 nt
	global_load_dwordx4 v[64:67], v203, s[12:13] offset:144 nt
	global_load_dwordx4 v[60:63], v204, s[12:13] nt
	global_load_dwordx4 v[56:59], v204, s[12:13] offset:16 nt
	global_load_dwordx4 v[52:55], v204, s[12:13] offset:128 nt
	global_load_dwordx4 v[48:51], v204, s[12:13] offset:144 nt
	global_load_dwordx4 v[44:47], v205, s[12:13] nt
	global_load_dwordx4 v[40:43], v205, s[12:13] offset:16 nt
	global_load_dwordx4 v[36:39], v205, s[12:13] offset:128 nt
	global_load_dwordx4 v[32:35], v205, s[12:13] offset:144 nt
	global_load_dwordx4 v[28:31], v206, s[12:13] nt
	global_load_dwordx4 v[24:27], v206, s[12:13] offset:16 nt
	global_load_dwordx4 v[20:23], v206, s[12:13] offset:128 nt
.Lxb_low:
	global_load_dwordx4 v[16:19], v206, s[12:13] offset:144 nt
	global_load_dwordx4 v[12:15], v207, s[12:13] nt
	global_load_dwordx4 v[8:11], v207, s[12:13] offset:16 nt
	global_load_dwordx4 v[4:7], v207, s[12:13] offset:128 nt
	global_load_dwordx4 v[0:3], v207, s[12:13] offset:144 nt
.Lxb_done:
	v_cmp_ne_u32_e64 s[0:1], 1, v240
	s_andn2_b64 vcc, exec, s[94:95]
	v_readfirstlane_b32 s26, v144
	s_cbranch_vccnz .LBB0_369
	s_ashr_i32 s4, s2, 31
	s_lshr_b32 s4, s4, 29
	s_add_i32 s6, s2, s4
	s_and_b32 s4, s6, -8
	s_sub_i32 s7, s2, s4
	s_cmp_gt_i32 s7, -1
	s_cbranch_scc0 .LBB0_366
	s_lshl_b32 s20, s7, 5
	s_cbranch_execz .LBB0_367
	s_branch .LBB0_368

.LBB0_369:
	s_add_u32 s6, s52, 0x100000
	s_addc_u32 s7, s53, 0
	s_and_b64 vcc, exec, s[0:1]
	s_cbranch_vccnz .LBB0_405
	v_ashrrev_i32_e32 v241, 31, v144
	v_lshrrev_b32_e32 v241, 26, v241
	v_add_u32_e32 v241, v144, v241
	v_ashrrev_i32_e32 v248, 6, v241
	v_bfe_i32 v241, v144, 27, 1
	v_lshlrev_b32_e32 v240, 4, v144
	v_lshrrev_b32_e32 v241, 22, v241
	v_add_u32_e32 v241, v240, v241
	v_and_b32_e32 v241, 0xfffffc00, v241
	v_sub_u32_e32 v241, v240, v241
	v_lshrrev_b32_e32 v242, 4, v241
	v_bitop3_b32 v241, v242, v241, 32 bitop3:0x6c
	v_ashrrev_i32_e32 v243, 31, v241
	v_lshrrev_b32_e32 v243, 26, v243
	v_add_u32_e32 v243, v241, v243
	v_ashrrev_i32_e32 v249, 6, v243
	v_and_b32_e32 v243, 0xc0, v243
	v_sub_u32_e32 v241, v241, v243
	v_mov_b32_e32 v243, 1
	v_lshlrev_b32_e32 v242, 3, v248
	v_lshlrev_b32_e32 v244, 5, v248
	v_ashrrev_i16_sdwa v241, v243, sext(v241) dst_sel:DWORD dst_unused:UNUSED_PAD src0_sel:DWORD src1_sel:BYTE_0
	v_and_b32_e32 v242, 0x1ffff0, v242
	v_and_b32_e32 v244, 32, v244
	v_bfe_i32 v250, v241, 0, 16
	v_add_u32_e32 v241, v244, v250
	v_add_lshl_u32 v242, v249, v242, 11
	v_add_u32_e32 v240, 0x2000, v240
	v_lshl_add_u32 v128, v241, 1, v242
	v_ashrrev_i32_e32 v241, 31, v240
	v_lshrrev_b32_e32 v241, 22, v241
	v_add_u32_e32 v241, v240, v241
	v_ashrrev_i32_e32 v251, 10, v241
	v_mul_i32_i24_e32 v241, 0x400, v251
	v_sub_u32_e32 v240, v240, v241
	v_lshrrev_b32_e32 v241, 4, v240
	v_bitop3_b32 v240, v241, v240, 32 bitop3:0x6c
	v_ashrrev_i32_e32 v242, 31, v240
	v_lshrrev_b32_e32 v242, 26, v242
	v_add_u32_e32 v242, v240, v242
	s_ashr_i32 s5, s26, 6
	s_ashr_i32 s45, s44, 31
	s_ashr_i32 s21, s20, 31
	s_ashr_i32 s4, s26, 8
	v_ashrrev_i32_e32 v252, 6, v242
	v_and_b32_e32 v242, 0xc0, v242
	s_lshl_b32 s56, s5, 10
	s_lshl_b64 s[22:23], s[44:45], 19
	s_lshl_b64 s[24:25], s[20:21], 19
	v_sub_u32_e32 v240, v240, v242
	s_add_u32 s48, s42, s24
	v_lshlrev_b32_e32 v241, 3, v251
	v_lshlrev_b32_e32 v244, 5, v251
	v_ashrrev_i16_sdwa v240, v243, sext(v240) dst_sel:DWORD dst_unused:UNUSED_PAD src0_sel:DWORD src1_sel:BYTE_0
	s_addc_u32 s49, s43, s25
	s_add_i32 s57, s56, 0
	v_and_b32_e32 v241, 0x1ffff0, v241
	v_and_b32_e32 v244, 32, v244
	v_bfe_i32 v253, v240, 0, 16
	s_add_i32 m0, s57, 0x10000
	v_add_u32_e32 v240, v244, v253
	v_add_lshl_u32 v241, v252, v241, 11
	global_load_lds_dwordx4 v128, s[48:49]
	s_add_i32 m0, s57, 0x12000
	v_lshl_add_u32 v130, v240, 1, v241
	s_add_u32 s24, s48, 0x40000
	global_load_lds_dwordx4 v130, s[48:49]
	s_addc_u32 s25, s49, 0
	s_add_i32 m0, s57, 0x14000
	v_mov_b32_e32 v129, 0
	global_load_lds_dwordx4 v128, s[24:25]
	s_add_i32 m0, s57, 0x16000
	s_add_u32 s46, s18, s22
	s_addc_u32 s47, s19, s23
	s_add_i32 s58, s57, 0x2000
	global_load_lds_dwordx4 v130, s[24:25]
	s_mov_b32 m0, s57
	s_add_u32 s22, s46, 0x40000
	global_load_lds_dwordx4 v128, s[46:47]
	s_mov_b32 m0, s58
	s_addc_u32 s23, s47, 0
	s_add_i32 s59, s57, 0x4000
	global_load_lds_dwordx4 v130, s[46:47]
	s_mov_b32 m0, s59
	s_add_i32 s60, s57, 0x6000
	global_load_lds_dwordx4 v128, s[22:23]
	s_mov_b32 m0, s60
	v_mov_b32_e32 v131, v129
	global_load_lds_dwordx4 v130, s[22:23]
	s_cmp_eq_u32 s4, 1
	s_mov_b32 s21, 0
	v_lshl_add_u64 v[246:247], s[48:49], 0, v[128:129]
	v_lshl_add_u64 v[244:245], s[48:49], 0, v[130:131]
	v_lshl_add_u64 v[240:241], s[46:47], 0, v[128:129]
	s_cselect_b64 s[22:23], -1, 0
	s_cmp_lg_u32 s4, 1
	v_lshl_add_u64 v[242:243], s[46:47], 0, v[130:131]
	s_cbranch_scc1 .LBB0_372
	s_barrier
.LBB0_372:
	s_mov_b64 s[24:25], 0x80
	s_lshl_b32 s8, s4, 13
	s_lshl_b32 s4, s5, 12
	s_add_i32 m0, s57, 0x18000
	v_lshl_add_u64 v[246:247], v[246:247], 0, s[24:25]
	s_and_b32 s9, s4, 0x3000
	s_waitcnt vmcnt(2)
	s_barrier
	global_load_lds_dwordx4 v[246:247], off
	v_lshl_add_u64 v[244:245], v[244:245], 0, s[24:25]
	s_add_i32 m0, s57, 0x1a000
	s_add_i32 s61, s57, 0x8000
	s_add_i32 s62, s57, 0xa000
	global_load_lds_dwordx4 v[244:245], off
	v_lshl_add_u64 v[240:241], v[240:241], 0, s[24:25]
	s_mov_b32 m0, s61
	s_add_u32 s4, s48, 0x40080
	global_load_lds_dwordx4 v[240:241], off
	v_lshl_add_u64 v[240:241], v[242:243], 0, s[24:25]
	s_mov_b32 m0, s62
	s_addc_u32 s5, s49, 0
	global_load_lds_dwordx4 v[240:241], off
	s_add_i32 m0, s57, 0x1c000
	v_lshl_add_u64 v[240:241], s[4:5], 0, v[128:129]
	global_load_lds_dwordx4 v[240:241], off
	v_lshl_add_u64 v[240:241], s[4:5], 0, v[130:131]
	s_add_i32 m0, s57, 0x1e000
	v_lshlrev_b32_e32 v243, 2, v144
	global_load_lds_dwordx4 v[240:241], off
	v_and_b32_e32 v240, 15, v144
	v_and_b32_e32 v241, 48, v144
	v_lshlrev_b32_e32 v240, 6, v240
	v_and_b32_e32 v243, 32, v243
	v_or_b32_e32 v242, v240, v241
	v_bitop3_b32 v240, v240, v243, v241 bitop3:0x36
	v_or_b32_e32 v145, s9, v240
	v_lshlrev_b32_e32 v240, 14, v248
	v_and_b32_e32 v240, 0xffff8000, v240
	v_bitop3_b32 v241, v242, s8, v243 bitop3:0xde
	v_lshl_add_u32 v240, v249, 11, v240
	v_and_b32_e32 v242, 1, v248
	v_lshl_or_b32 v240, v242, 6, v240
	v_lshl_add_u32 v132, v250, 1, v240
	v_lshlrev_b32_e32 v240, 14, v251
	v_and_b32_e32 v240, 0xffff8000, v240
	s_waitcnt vmcnt(6)
	s_cmpk_lt_u32 s26, 0x100
	v_lshl_add_u32 v240, v252, 11, v240
	v_and_b32_e32 v242, 1, v251
	s_cselect_b64 s[26:27], -1, 0
	v_lshl_or_b32 v240, v242, 6, v240
	s_add_i32 s66, 0, 0x10000
	s_add_i32 s67, 0, 0x14000
	s_ashr_i32 s63, s10, 31
	s_mov_b32 s64, s10
	s_ashr_i32 s65, s2, 31
	v_mov_b32_e32 v133, v129
	v_lshl_add_u32 v134, v253, 1, v240
	v_mov_b32_e32 v135, v129
	v_mov_b64_e32 v[136:137], 0x100
	v_mov_b64_e32 v[138:139], 0xff
	v_add_u32_e32 v146, s66, v145
	v_add_u32_e32 v147, s67, v145
	v_add_u32_e32 v148, 0, v241
	s_mov_b32 s68, 0
	s_barrier
	s_branch .LBB0_375

.LBB0_380:
	s_ashr_i32 s8, s36, 3
	s_add_i32 s8, s38, s8
	s_ashr_i32 s9, s8, 31
	s_lshr_b32 s9, s9, 27
	s_add_i32 s9, s8, s9
	s_ashr_i32 s28, s9, 5
	s_lshl_b32 s29, s28, 3
	s_sub_i32 s28, 64, s29
	s_min_i32 s36, s28, 8
	s_abs_i32 s28, s36
	v_cvt_f32_u32_e32 v240, s28
	s_sub_i32 s38, 0, s28
	s_andn2_b32 s9, s9, 31
	s_sub_i32 s8, s8, s9
	v_rcp_iflag_f32_e32 v240, v240
	s_abs_i32 s9, s8
	s_xor_b32 s37, s8, s36
	s_ashr_i32 s37, s37, 31
	v_mul_f32_e32 v240, 0x4f7ffffe, v240
	v_cvt_u32_f32_e32 v240, v240
	s_nop 0
	v_readfirstlane_b32 s39, v240
	s_mul_i32 s38, s38, s39
	s_mul_hi_u32 s38, s39, s38
	s_add_i32 s39, s39, s38
	s_mul_hi_u32 s38, s9, s39
	s_mul_i32 s39, s38, s28
	s_sub_i32 s9, s9, s39
	s_add_i32 s40, s38, 1
	s_sub_i32 s39, s9, s28
	s_cmp_ge_u32 s9, s28
	s_cselect_b32 s38, s40, s38
	s_cselect_b32 s9, s39, s9
	s_add_i32 s39, s38, 1
	s_cmp_ge_u32 s9, s28
	s_cselect_b32 s9, s39, s38
	s_xor_b32 s9, s9, s37
	s_sub_i32 s28, s9, s37
	s_mul_i32 s9, s28, s36
	s_sub_i32 s8, s8, s9
	s_add_i32 s36, s29, s8
.LBB0_381:
	s_ashr_i32 s37, s36, 31
	s_lshl_b64 s[38:39], s[36:37], 19
	s_add_u32 s38, s18, s38
	s_addc_u32 s39, s19, s39
	s_and_b64 s[40:41], s[4:5], exec
	s_cselect_b32 s37, s39, s47
	s_cselect_b32 s45, s38, s46
	s_ashr_i32 s29, s28, 31
	s_lshl_b64 s[40:41], s[28:29], 19
	s_add_u32 s40, s42, s40
	s_addc_u32 s41, s43, s41
	s_and_b64 s[50:51], s[4:5], exec
	s_cselect_b32 s29, s41, s49
	s_cselect_b32 s69, s40, s48
	s_add_u32 s46, s46, 0x40080
	s_addc_u32 s47, s47, 0
	s_add_u32 s70, s48, 0x100
	s_addc_u32 s71, s49, 0
	s_mov_b32 s72, -2
	s_waitcnt lgkmcnt(0)
	s_waitcnt vmcnt(0)

.LBB0_385:
	v_mov_b32_e32 v140, v144
	s_lshl_b32 s9, s44, 8
	v_readfirstlane_b32 s8, v140
	s_bfe_u32 s29, s8, 0x20006
	s_ashr_i32 s8, s8, 2
	s_andn2_b32 s8, s8, 63
	s_add_i32 s8, s8, s9
	v_and_or_b32 v142, v140, 15, s8
	s_lshl_b32 s8, s20, 8
	s_lshl_b32 s9, s29, 6
	v_bfe_u32 v149, v140, 4, 2
	s_or_b32 s8, s9, s8
	v_lshl_or_b32 v140, v149, 3, s8
	v_ashrrev_i32_e32 v143, 31, v142
	v_ashrrev_i32_e32 v141, 31, v140
	v_lshlrev_b64 v[150:151], 10, v[142:143]
	v_lshl_add_u64 v[158:159], v[150:151], 0, v[140:141]
	v_lshl_add_u64 v[160:161], v[158:159], 2, s[12:13]
	v_lshl_add_u64 v[158:159], v[158:159], 1, s[16:17]
	s_lshl_b32 s44, s20, 2
	v_cmp_eq_u32_e32 vcc, 0, v149
	s_ashr_i32 s45, s44, 31
	v_mov_b64_e32 v[152:153], v[126:127]
	v_mov_b64_e32 v[150:151], v[124:125]
	v_mov_b64_e32 v[156:157], v[122:123]
	v_mov_b64_e32 v[154:155], v[120:121]
	v_cvt_pk_bf16_f32 v120, v150, v151
	v_cvt_pk_bf16_f32 v121, v152, v153
	v_cvt_pk_bf16_f32 v122, v154, v155
	v_cvt_pk_bf16_f32 v123, v156, v157
	global_store_dwordx4 v[158:159], v[120:123], off
	s_nop 0
	v_mul_f32_e32 v151, v151, v151
	v_mul_f32_e32 v153, v153, v153
	v_mul_f32_e32 v155, v155, v155
	v_mul_f32_e32 v157, v157, v157
	v_fmac_f32_e32 v151, v150, v150
	v_fmac_f32_e32 v153, v152, v152
	v_fmac_f32_e32 v155, v154, v154
	v_fmac_f32_e32 v157, v156, v156
	v_add_f32_e32 v150, v151, v153
	v_add_f32_e32 v151, v155, v157
	v_add_f32_e32 v150, v150, v151
	v_mov_b64_e32 v[120:121], v[114:115]
	v_mov_b64_e32 v[122:123], v[112:113]
	v_mul_f32_e32 v112, v117, v117
	v_mul_f32_e32 v113, v119, v119
	v_mul_f32_e32 v114, v123, v123
	v_mul_f32_e32 v115, v121, v121
	v_fmac_f32_e32 v112, v116, v116
	v_fmac_f32_e32 v113, v118, v118
	v_fmac_f32_e32 v114, v122, v122
	v_fmac_f32_e32 v115, v120, v120
	v_add_f32_e32 v112, v112, v113
	v_add_f32_e32 v113, v114, v115
	v_add_f32_e32 v112, v112, v113
	v_add_f32_e32 v112, v150, v112
	ds_bpermute_b32 v113, v193, v112
	v_cvt_pk_bf16_f32 v114, v116, v117
	v_cvt_pk_bf16_f32 v115, v118, v119
	v_cvt_pk_bf16_f32 v116, v122, v123
	v_cvt_pk_bf16_f32 v117, v120, v121
	s_waitcnt lgkmcnt(0)
	v_add_f32_e32 v112, v112, v113
	ds_bpermute_b32 v113, v194, v112
	global_store_dwordx4 v[158:159], v[114:117], off offset:64
	s_and_saveexec_b64 s[46:47], vcc
	s_cbranch_execz .LBB0_387
	v_lshlrev_b64 v[114:115], 6, v[142:143]
	v_lshl_add_u64 v[114:115], s[6:7], 0, v[114:115]
	v_lshl_add_u64 v[114:115], s[44:45], 2, v[114:115]
	s_lshl_b32 s20, s29, 2
	v_lshl_add_u64 v[114:115], v[114:115], 0, s[20:21]
	s_waitcnt lgkmcnt(0)
	v_add_f32_e32 v112, v112, v113
	global_store_dword v[114:115], v112, off
.LBB0_387:
	s_or_b64 exec, exec, s[46:47]
	v_or_b32_e32 v112, 16, v142
	s_waitcnt lgkmcnt(0)
	v_ashrrev_i32_e32 v113, 31, v112
	v_lshlrev_b64 v[114:115], 10, v[112:113]
	v_lshl_add_u64 v[122:123], v[114:115], 0, v[140:141]
	v_lshl_add_u64 v[124:125], v[122:123], 2, s[12:13]
	v_lshl_add_u64 v[122:123], v[122:123], 1, s[16:17]
	v_mov_b64_e32 v[116:117], v[110:111]
	v_mov_b64_e32 v[114:115], v[108:109]
	v_mov_b64_e32 v[120:121], v[106:107]
	v_mov_b64_e32 v[118:119], v[104:105]
	v_cvt_pk_bf16_f32 v104, v114, v115
	v_cvt_pk_bf16_f32 v105, v116, v117
	v_cvt_pk_bf16_f32 v106, v118, v119
	v_cvt_pk_bf16_f32 v107, v120, v121
	global_store_dwordx4 v[122:123], v[104:107], off
	s_nop 0
	v_mul_f32_e32 v115, v115, v115
	v_mul_f32_e32 v117, v117, v117
	v_mul_f32_e32 v119, v119, v119
	v_mul_f32_e32 v121, v121, v121
	v_fmac_f32_e32 v115, v114, v114
	v_fmac_f32_e32 v117, v116, v116
	v_fmac_f32_e32 v119, v118, v118
	v_fmac_f32_e32 v121, v120, v120
	v_add_f32_e32 v114, v115, v117
	v_add_f32_e32 v115, v119, v121
	v_add_f32_e32 v114, v114, v115
	v_mov_b64_e32 v[104:105], v[98:99]
	v_mov_b64_e32 v[106:107], v[96:97]
	v_mul_f32_e32 v96, v101, v101
	v_mul_f32_e32 v97, v103, v103
	v_mul_f32_e32 v98, v107, v107
	v_mul_f32_e32 v99, v105, v105
	v_fmac_f32_e32 v96, v100, v100
	v_fmac_f32_e32 v97, v102, v102
	v_fmac_f32_e32 v98, v106, v106
	v_fmac_f32_e32 v99, v104, v104
	v_add_f32_e32 v96, v96, v97
	v_add_f32_e32 v97, v98, v99
	v_add_f32_e32 v96, v96, v97
	v_add_f32_e32 v96, v114, v96
	ds_bpermute_b32 v97, v193, v96
	v_cvt_pk_bf16_f32 v98, v100, v101
	v_cvt_pk_bf16_f32 v99, v102, v103
	v_cvt_pk_bf16_f32 v100, v106, v107
	v_cvt_pk_bf16_f32 v101, v104, v105
	s_waitcnt lgkmcnt(0)
	v_add_f32_e32 v96, v96, v97
	ds_bpermute_b32 v97, v194, v96
	global_store_dwordx4 v[122:123], v[98:101], off offset:64
	s_and_saveexec_b64 s[46:47], vcc
	s_cbranch_execz .LBB0_389
	v_lshlrev_b64 v[98:99], 6, v[112:113]
	v_lshl_add_u64 v[98:99], s[6:7], 0, v[98:99]
	v_lshl_add_u64 v[98:99], s[44:45], 2, v[98:99]
	s_lshl_b32 s20, s29, 2
	v_lshl_add_u64 v[98:99], v[98:99], 0, s[20:21]
	s_waitcnt lgkmcnt(0)
	v_add_f32_e32 v96, v96, v97
	global_store_dword v[98:99], v96, off
.LBB0_389:
	s_or_b64 exec, exec, s[46:47]
	v_or_b32_e32 v96, 32, v142
	s_waitcnt lgkmcnt(0)
	v_ashrrev_i32_e32 v97, 31, v96
	v_lshlrev_b64 v[98:99], 10, v[96:97]
	v_lshl_add_u64 v[106:107], v[98:99], 0, v[140:141]
	v_lshl_add_u64 v[108:109], v[106:107], 2, s[12:13]
	v_lshl_add_u64 v[106:107], v[106:107], 1, s[16:17]
	v_mov_b64_e32 v[100:101], v[94:95]
	v_mov_b64_e32 v[98:99], v[92:93]
	v_mov_b64_e32 v[104:105], v[90:91]
	v_mov_b64_e32 v[102:103], v[88:89]
	v_cvt_pk_bf16_f32 v88, v98, v99
	v_cvt_pk_bf16_f32 v89, v100, v101
	v_cvt_pk_bf16_f32 v90, v102, v103
	v_cvt_pk_bf16_f32 v91, v104, v105
	global_store_dwordx4 v[106:107], v[88:91], off
	s_nop 0
	v_mul_f32_e32 v99, v99, v99
	v_mul_f32_e32 v101, v101, v101
	v_mul_f32_e32 v103, v103, v103
	v_mul_f32_e32 v105, v105, v105
	v_fmac_f32_e32 v99, v98, v98
	v_fmac_f32_e32 v101, v100, v100
	v_fmac_f32_e32 v103, v102, v102
	v_fmac_f32_e32 v105, v104, v104
	v_add_f32_e32 v98, v99, v101
	v_add_f32_e32 v99, v103, v105
	v_add_f32_e32 v98, v98, v99
	v_mov_b64_e32 v[88:89], v[82:83]
	v_mov_b64_e32 v[90:91], v[80:81]
	v_mul_f32_e32 v80, v85, v85
	v_mul_f32_e32 v81, v87, v87
	v_mul_f32_e32 v82, v91, v91
	v_mul_f32_e32 v83, v89, v89
	v_fmac_f32_e32 v80, v84, v84
	v_fmac_f32_e32 v81, v86, v86
	v_fmac_f32_e32 v82, v90, v90
	v_fmac_f32_e32 v83, v88, v88
	v_add_f32_e32 v80, v80, v81
	v_add_f32_e32 v81, v82, v83
	v_add_f32_e32 v80, v80, v81
	v_add_f32_e32 v80, v98, v80
	ds_bpermute_b32 v81, v193, v80
	v_cvt_pk_bf16_f32 v82, v84, v85
	v_cvt_pk_bf16_f32 v83, v86, v87
	v_cvt_pk_bf16_f32 v84, v90, v91
	v_cvt_pk_bf16_f32 v85, v88, v89
	s_waitcnt lgkmcnt(0)
	v_add_f32_e32 v80, v80, v81
	ds_bpermute_b32 v81, v194, v80
	global_store_dwordx4 v[106:107], v[82:85], off offset:64
	s_and_saveexec_b64 s[46:47], vcc
	s_cbranch_execz .LBB0_391
	v_lshlrev_b64 v[82:83], 6, v[96:97]
	v_lshl_add_u64 v[82:83], s[6:7], 0, v[82:83]
	v_lshl_add_u64 v[82:83], s[44:45], 2, v[82:83]
	s_lshl_b32 s20, s29, 2
	v_lshl_add_u64 v[82:83], v[82:83], 0, s[20:21]
	s_waitcnt lgkmcnt(0)
	v_add_f32_e32 v80, v80, v81
	global_store_dword v[82:83], v80, off
.LBB0_391:
	s_or_b64 exec, exec, s[46:47]
	v_or_b32_e32 v80, 48, v142
	s_waitcnt lgkmcnt(0)
	v_ashrrev_i32_e32 v81, 31, v80
	v_lshlrev_b64 v[82:83], 10, v[80:81]
	v_lshl_add_u64 v[90:91], v[82:83], 0, v[140:141]
	v_lshl_add_u64 v[92:93], v[90:91], 2, s[12:13]
	v_lshl_add_u64 v[90:91], v[90:91], 1, s[16:17]
	v_mov_b64_e32 v[84:85], v[78:79]
	v_mov_b64_e32 v[82:83], v[76:77]
	v_mov_b64_e32 v[88:89], v[74:75]
	v_mov_b64_e32 v[86:87], v[72:73]
	v_cvt_pk_bf16_f32 v72, v82, v83
	v_cvt_pk_bf16_f32 v73, v84, v85
	v_cvt_pk_bf16_f32 v74, v86, v87
	v_cvt_pk_bf16_f32 v75, v88, v89
	global_store_dwordx4 v[90:91], v[72:75], off
	s_nop 0
	v_mul_f32_e32 v83, v83, v83
	v_mul_f32_e32 v85, v85, v85
	v_mul_f32_e32 v87, v87, v87
	v_mul_f32_e32 v89, v89, v89
	v_fmac_f32_e32 v83, v82, v82
	v_fmac_f32_e32 v85, v84, v84
	v_fmac_f32_e32 v87, v86, v86
	v_fmac_f32_e32 v89, v88, v88
	v_add_f32_e32 v82, v83, v85
	v_add_f32_e32 v83, v87, v89
	v_add_f32_e32 v82, v82, v83
	v_mov_b64_e32 v[72:73], v[66:67]
	v_mov_b64_e32 v[74:75], v[64:65]
	v_mul_f32_e32 v64, v69, v69
	v_mul_f32_e32 v65, v71, v71
	v_mul_f32_e32 v66, v75, v75
	v_mul_f32_e32 v67, v73, v73
	v_fmac_f32_e32 v64, v68, v68
	v_fmac_f32_e32 v65, v70, v70
	v_fmac_f32_e32 v66, v74, v74
	v_fmac_f32_e32 v67, v72, v72
	v_add_f32_e32 v64, v64, v65
	v_add_f32_e32 v65, v66, v67
	v_add_f32_e32 v64, v64, v65
	v_add_f32_e32 v64, v82, v64
	ds_bpermute_b32 v65, v193, v64
	v_cvt_pk_bf16_f32 v66, v68, v69
	v_cvt_pk_bf16_f32 v67, v70, v71
	v_cvt_pk_bf16_f32 v68, v74, v75
	v_cvt_pk_bf16_f32 v69, v72, v73
	s_waitcnt lgkmcnt(0)
	v_add_f32_e32 v64, v64, v65
	ds_bpermute_b32 v65, v194, v64
	global_store_dwordx4 v[90:91], v[66:69], off offset:64
	s_and_saveexec_b64 s[46:47], vcc
	s_cbranch_execz .LBB0_393
	v_lshlrev_b64 v[66:67], 6, v[80:81]
	v_lshl_add_u64 v[66:67], s[6:7], 0, v[66:67]
	v_lshl_add_u64 v[66:67], s[44:45], 2, v[66:67]
	s_lshl_b32 s20, s29, 2
	v_lshl_add_u64 v[66:67], v[66:67], 0, s[20:21]
	s_waitcnt lgkmcnt(0)
	v_add_f32_e32 v64, v64, v65
	global_store_dword v[66:67], v64, off
.LBB0_393:
	s_or_b64 exec, exec, s[46:47]
	v_add_u32_e32 v64, 0x80, v142
	s_waitcnt lgkmcnt(0)
	v_ashrrev_i32_e32 v65, 31, v64
	v_lshlrev_b64 v[66:67], 10, v[64:65]
	v_lshl_add_u64 v[74:75], v[66:67], 0, v[140:141]
	v_lshl_add_u64 v[76:77], v[74:75], 2, s[12:13]
	v_lshl_add_u64 v[74:75], v[74:75], 1, s[16:17]
	v_mov_b64_e32 v[68:69], v[62:63]
	v_mov_b64_e32 v[66:67], v[60:61]
	v_mov_b64_e32 v[72:73], v[58:59]
	v_mov_b64_e32 v[70:71], v[56:57]
	v_cvt_pk_bf16_f32 v56, v66, v67
	v_cvt_pk_bf16_f32 v57, v68, v69
	v_cvt_pk_bf16_f32 v58, v70, v71
	v_cvt_pk_bf16_f32 v59, v72, v73
	global_store_dwordx4 v[74:75], v[56:59], off
	s_nop 0
	v_mul_f32_e32 v67, v67, v67
	v_mul_f32_e32 v69, v69, v69
	v_mul_f32_e32 v71, v71, v71
	v_mul_f32_e32 v73, v73, v73
	v_fmac_f32_e32 v67, v66, v66
	v_fmac_f32_e32 v69, v68, v68
	v_fmac_f32_e32 v71, v70, v70
	v_fmac_f32_e32 v73, v72, v72
	v_add_f32_e32 v66, v67, v69
	v_add_f32_e32 v67, v71, v73
	v_add_f32_e32 v66, v66, v67
	v_mov_b64_e32 v[56:57], v[50:51]
	v_mov_b64_e32 v[58:59], v[48:49]
	v_mul_f32_e32 v48, v53, v53
	v_mul_f32_e32 v49, v55, v55
	v_mul_f32_e32 v50, v59, v59
	v_mul_f32_e32 v51, v57, v57
	v_fmac_f32_e32 v48, v52, v52
	v_fmac_f32_e32 v49, v54, v54
	v_fmac_f32_e32 v50, v58, v58
	v_fmac_f32_e32 v51, v56, v56
	v_add_f32_e32 v48, v48, v49
	v_add_f32_e32 v49, v50, v51
	v_add_f32_e32 v48, v48, v49
	v_add_f32_e32 v48, v66, v48
	ds_bpermute_b32 v49, v193, v48
	v_cvt_pk_bf16_f32 v50, v52, v53
	v_cvt_pk_bf16_f32 v51, v54, v55
	v_cvt_pk_bf16_f32 v52, v58, v59
	v_cvt_pk_bf16_f32 v53, v56, v57
	s_waitcnt lgkmcnt(0)
	v_add_f32_e32 v48, v48, v49
	ds_bpermute_b32 v49, v194, v48
	global_store_dwordx4 v[74:75], v[50:53], off offset:64
	s_and_saveexec_b64 s[46:47], vcc
	s_cbranch_execz .LBB0_395
	v_lshlrev_b64 v[50:51], 6, v[64:65]
	v_lshl_add_u64 v[50:51], s[6:7], 0, v[50:51]
	v_lshl_add_u64 v[50:51], s[44:45], 2, v[50:51]
	s_lshl_b32 s20, s29, 2
	v_lshl_add_u64 v[50:51], v[50:51], 0, s[20:21]
	s_waitcnt lgkmcnt(0)
	v_add_f32_e32 v48, v48, v49
	global_store_dword v[50:51], v48, off
.LBB0_395:
	s_or_b64 exec, exec, s[46:47]
	v_add_u32_e32 v48, 0x90, v142
	s_waitcnt lgkmcnt(0)
	v_ashrrev_i32_e32 v49, 31, v48
	v_lshlrev_b64 v[50:51], 10, v[48:49]
	v_lshl_add_u64 v[58:59], v[50:51], 0, v[140:141]
	v_lshl_add_u64 v[60:61], v[58:59], 2, s[12:13]
	v_lshl_add_u64 v[58:59], v[58:59], 1, s[16:17]
	v_mov_b64_e32 v[52:53], v[46:47]
	v_mov_b64_e32 v[50:51], v[44:45]
	v_mov_b64_e32 v[56:57], v[42:43]
	v_mov_b64_e32 v[54:55], v[40:41]
	v_cvt_pk_bf16_f32 v40, v50, v51
	v_cvt_pk_bf16_f32 v41, v52, v53
	v_cvt_pk_bf16_f32 v42, v54, v55
	v_cvt_pk_bf16_f32 v43, v56, v57
	global_store_dwordx4 v[58:59], v[40:43], off
	s_nop 0
	v_mul_f32_e32 v51, v51, v51
	v_mul_f32_e32 v53, v53, v53
	v_mul_f32_e32 v55, v55, v55
	v_mul_f32_e32 v57, v57, v57
	v_fmac_f32_e32 v51, v50, v50
	v_fmac_f32_e32 v53, v52, v52
	v_fmac_f32_e32 v55, v54, v54
	v_fmac_f32_e32 v57, v56, v56
	v_add_f32_e32 v50, v51, v53
	v_add_f32_e32 v51, v55, v57
	v_add_f32_e32 v50, v50, v51
	v_mov_b64_e32 v[40:41], v[34:35]
	v_mov_b64_e32 v[42:43], v[32:33]
	v_mul_f32_e32 v32, v37, v37
	v_mul_f32_e32 v33, v39, v39
	v_mul_f32_e32 v34, v43, v43
	v_mul_f32_e32 v35, v41, v41
	v_fmac_f32_e32 v32, v36, v36
	v_fmac_f32_e32 v33, v38, v38
	v_fmac_f32_e32 v34, v42, v42
	v_fmac_f32_e32 v35, v40, v40
	v_add_f32_e32 v32, v32, v33
	v_add_f32_e32 v33, v34, v35
	v_add_f32_e32 v32, v32, v33
	v_add_f32_e32 v32, v50, v32
	ds_bpermute_b32 v33, v193, v32
	v_cvt_pk_bf16_f32 v34, v36, v37
	v_cvt_pk_bf16_f32 v35, v38, v39
	v_cvt_pk_bf16_f32 v36, v42, v43
	v_cvt_pk_bf16_f32 v37, v40, v41
	s_waitcnt lgkmcnt(0)
	v_add_f32_e32 v32, v32, v33
	ds_bpermute_b32 v33, v194, v32
	global_store_dwordx4 v[58:59], v[34:37], off offset:64
	s_and_saveexec_b64 s[46:47], vcc
	s_cbranch_execz .LBB0_397
	v_lshlrev_b64 v[34:35], 6, v[48:49]
	v_lshl_add_u64 v[34:35], s[6:7], 0, v[34:35]
	v_lshl_add_u64 v[34:35], s[44:45], 2, v[34:35]
	s_lshl_b32 s20, s29, 2
	v_lshl_add_u64 v[34:35], v[34:35], 0, s[20:21]
	s_waitcnt lgkmcnt(0)
	v_add_f32_e32 v32, v32, v33
	global_store_dword v[34:35], v32, off
.LBB0_397:
	s_or_b64 exec, exec, s[46:47]
	v_add_u32_e32 v32, 0xa0, v142
	s_waitcnt lgkmcnt(0)
	v_ashrrev_i32_e32 v33, 31, v32
	v_lshlrev_b64 v[34:35], 10, v[32:33]
	v_lshl_add_u64 v[42:43], v[34:35], 0, v[140:141]
	v_lshl_add_u64 v[44:45], v[42:43], 2, s[12:13]
	v_lshl_add_u64 v[42:43], v[42:43], 1, s[16:17]
	v_mov_b64_e32 v[36:37], v[30:31]
	v_mov_b64_e32 v[34:35], v[28:29]
	v_mov_b64_e32 v[40:41], v[26:27]
	v_mov_b64_e32 v[38:39], v[24:25]
	v_cvt_pk_bf16_f32 v24, v34, v35
	v_cvt_pk_bf16_f32 v25, v36, v37
	v_cvt_pk_bf16_f32 v26, v38, v39
	v_cvt_pk_bf16_f32 v27, v40, v41
	global_store_dwordx4 v[42:43], v[24:27], off
	s_nop 0
	v_mul_f32_e32 v35, v35, v35
	v_mul_f32_e32 v37, v37, v37
	v_mul_f32_e32 v39, v39, v39
	v_mul_f32_e32 v41, v41, v41
	v_fmac_f32_e32 v35, v34, v34
	v_fmac_f32_e32 v37, v36, v36
	v_fmac_f32_e32 v39, v38, v38
	v_fmac_f32_e32 v41, v40, v40
	v_add_f32_e32 v34, v35, v37
	v_add_f32_e32 v35, v39, v41
	v_add_f32_e32 v34, v34, v35
	v_mov_b64_e32 v[24:25], v[18:19]
	v_mov_b64_e32 v[26:27], v[16:17]
	v_mul_f32_e32 v16, v21, v21
	v_mul_f32_e32 v17, v23, v23
	v_mul_f32_e32 v18, v27, v27
	v_mul_f32_e32 v19, v25, v25
	v_fmac_f32_e32 v16, v20, v20
	v_fmac_f32_e32 v17, v22, v22
	v_fmac_f32_e32 v18, v26, v26
	v_fmac_f32_e32 v19, v24, v24
	v_add_f32_e32 v16, v16, v17
	v_add_f32_e32 v17, v18, v19
	v_add_f32_e32 v16, v16, v17
	v_add_f32_e32 v16, v34, v16
	ds_bpermute_b32 v17, v193, v16
	v_cvt_pk_bf16_f32 v18, v20, v21
	v_cvt_pk_bf16_f32 v19, v22, v23
	v_cvt_pk_bf16_f32 v20, v26, v27
	v_cvt_pk_bf16_f32 v21, v24, v25
	s_waitcnt lgkmcnt(0)
	v_add_f32_e32 v16, v16, v17
	ds_bpermute_b32 v17, v194, v16
	global_store_dwordx4 v[42:43], v[18:21], off offset:64
	s_and_saveexec_b64 s[46:47], vcc
	s_cbranch_execz .LBB0_399
	v_lshlrev_b64 v[18:19], 6, v[32:33]
	v_lshl_add_u64 v[18:19], s[6:7], 0, v[18:19]
	v_lshl_add_u64 v[18:19], s[44:45], 2, v[18:19]
	s_lshl_b32 s20, s29, 2
	v_lshl_add_u64 v[18:19], v[18:19], 0, s[20:21]
	s_waitcnt lgkmcnt(0)
	v_add_f32_e32 v16, v16, v17
	global_store_dword v[18:19], v16, off
.LBB0_399:
	s_or_b64 exec, exec, s[46:47]
	v_add_u32_e32 v16, 0xb0, v142
	s_waitcnt lgkmcnt(0)
	v_ashrrev_i32_e32 v17, 31, v16
	v_lshlrev_b64 v[18:19], 10, v[16:17]
	v_lshl_add_u64 v[26:27], v[18:19], 0, v[140:141]
	v_lshl_add_u64 v[28:29], v[26:27], 2, s[12:13]
	v_lshl_add_u64 v[26:27], v[26:27], 1, s[16:17]
	v_mov_b64_e32 v[20:21], v[14:15]
	v_mov_b64_e32 v[18:19], v[12:13]
	v_mov_b64_e32 v[24:25], v[10:11]
	v_mov_b64_e32 v[22:23], v[8:9]
	v_cvt_pk_bf16_f32 v8, v18, v19
	v_cvt_pk_bf16_f32 v9, v20, v21
	v_cvt_pk_bf16_f32 v10, v22, v23
	v_cvt_pk_bf16_f32 v11, v24, v25
	global_store_dwordx4 v[26:27], v[8:11], off
	s_nop 0
	v_mul_f32_e32 v19, v19, v19
	v_mul_f32_e32 v21, v21, v21
	v_mul_f32_e32 v23, v23, v23
	v_mul_f32_e32 v25, v25, v25
	v_fmac_f32_e32 v19, v18, v18
	v_fmac_f32_e32 v21, v20, v20
	v_fmac_f32_e32 v23, v22, v22
	v_fmac_f32_e32 v25, v24, v24
	v_add_f32_e32 v18, v19, v21
	v_add_f32_e32 v19, v23, v25
	v_add_f32_e32 v18, v18, v19
	v_mov_b64_e32 v[8:9], v[2:3]
	v_mov_b64_e32 v[10:11], v[0:1]
	v_mul_f32_e32 v0, v5, v5
	v_mul_f32_e32 v1, v7, v7
	v_mul_f32_e32 v2, v11, v11
	v_mul_f32_e32 v3, v9, v9
	v_fmac_f32_e32 v0, v4, v4
	v_fmac_f32_e32 v1, v6, v6
	v_fmac_f32_e32 v2, v10, v10
	v_fmac_f32_e32 v3, v8, v8
	v_add_f32_e32 v0, v0, v1
	v_add_f32_e32 v1, v2, v3
	v_add_f32_e32 v0, v0, v1
	v_add_f32_e32 v0, v18, v0
	ds_bpermute_b32 v1, v193, v0
	v_cvt_pk_bf16_f32 v2, v4, v5
	v_cvt_pk_bf16_f32 v3, v6, v7
	v_cvt_pk_bf16_f32 v4, v10, v11
	v_cvt_pk_bf16_f32 v5, v8, v9
	s_waitcnt lgkmcnt(0)
	v_add_f32_e32 v0, v0, v1
	ds_bpermute_b32 v1, v194, v0
	global_store_dwordx4 v[26:27], v[2:5], off offset:64
	s_and_saveexec_b64 s[46:47], vcc
	s_cbranch_execz .LBB0_401
	v_lshlrev_b64 v[2:3], 6, v[16:17]
	v_lshl_add_u64 v[2:3], s[6:7], 0, v[2:3]
	v_lshl_add_u64 v[2:3], s[44:45], 2, v[2:3]
	s_lshl_b32 s20, s29, 2
	v_lshl_add_u64 v[2:3], v[2:3], 0, s[20:21]
	s_waitcnt lgkmcnt(0)
	v_add_f32_e32 v0, v0, v1
	global_store_dword v[2:3], v0, off
